# MF=2 DMA GEMM loops: DMA issue spread over the first 4 MFMAs of the previous step and fragment reads over the next 4 (front interleave), rest of MFMAs back to back
# speedup vs baseline: 1.0069x; 1.0069x over previous
; #define MFMA32(a, b, c) __builtin_amdgcn_mfma_f32_32x32x16_bf16((a), (b), (c), 0, 0, 0)
; template <int MF, int BK, class Epi>
; DI void gemm_phase_t(char* lds, const GemmDesc g, const Epi epi) {
;     ...
;     for (int kt = 0; kt < nk; ++kt) {
;       __syncthreads();
;       const u16* sA = sbase + (kt & 1) * STG;
;       const u16* sB = sA + BM * LS;
;       if (kt + 1 < nk) {
;         u16* nA = sbase + ((kt + 1) & 1) * STG;
; #pragma unroll
;         for (int j = 0; j < APT; ++j) *(u32x4*)(nA + (lr + RSTEP * j) * LS + lc * 8) = ra[j];
; #pragma unroll
;         for (int j = 0; j < BPT; ++j) *(u32x4*)(nA + BM * LS + (lr + RSTEP * j) * LS + lc * 8) = rb[j];
;         if (kt + 2 < nk) {
; #pragma unroll
;           for (int j = 0; j < APT; ++j) ra[j] = *(const u32x4*)(Ap + (size_t)j * RSTEP * g.lda + (kt + 2) * BK);
; #pragma unroll
;           for (int j = 0; j < BPT; ++j) rb[j] = *(const u32x4*)(Bp + (size_t)j * RSTEP * g.ldb + (kt + 2) * BK);
;         }
;       }
;       bf16x8 af[NKK][MF], bfr[NKK][2];
; #pragma unroll
;       for (int kk = 0; kk < NKK; ++kk) {
; #pragma unroll
;         for (int ni = 0; ni < 2; ++ni) bfr[kk][ni] = *(const bf16x8*)(sB + (wn * 64 + ni * 32 + l31) * LS + kk * 16 + h * 8);
; #pragma unroll
;         for (int mi = 0; mi < MF; ++mi) af[kk][mi] = *(const bf16x8*)(sA + (wm * (MF * 32) + mi * 32 + l31) * LS + kk * 16 + h * 8);
;       }
;       __builtin_amdgcn_sched_barrier(0);
; #pragma unroll
;       for (int kk = 0; kk < NKK; ++kk)
; #pragma unroll
;         for (int mi = 0; mi < MF; ++mi)
; #pragma unroll
;           for (int ni = 0; ni < 2; ++ni) acc[mi][ni] = MFMA32(bfr[kk][ni], af[kk][mi], acc[mi][ni]);
;     }
.Ldma_dn_loop:
	s_waitcnt vmcnt(0)
	s_waitcnt lgkmcnt(0)
	s_barrier
	v_mfma_f32_32x32x16_bf16 v[52:67], v[68:71], v[76:79], v[52:67]
	s_add_i32 m0, s100, 0x0
	s_nop 0
	global_load_lds_dwordx4 v108, s[12:13]
	s_add_i32 m0, s100, 0x1000
	s_nop 0
	global_load_lds_dwordx4 v109, s[12:13]
	v_mfma_f32_32x32x16_bf16 v[36:51], v[72:75], v[76:79], v[36:51]
	s_add_i32 m0, s100, 0x2000
	s_nop 0
	global_load_lds_dwordx4 v110, s[12:13]
	s_add_i32 m0, s100, 0x3000
	s_nop 0
	global_load_lds_dwordx4 v111, s[12:13]
	v_mfma_f32_32x32x16_bf16 v[20:35], v[68:71], v[80:83], v[20:35]
	s_add_i32 m0, s100, 0x4000
	s_nop 0
	global_load_lds_dwordx4 v108, s[14:15]
	s_add_i32 m0, s100, 0x5000
	s_nop 0
	global_load_lds_dwordx4 v109, s[14:15]
	v_mfma_f32_32x32x16_bf16 v[4:19], v[72:75], v[80:83], v[4:19]
	s_add_i32 m0, s100, 0x6000
	s_nop 0
	global_load_lds_dwordx4 v110, s[14:15]
	s_add_i32 m0, s100, 0x7000
	s_nop 0
	global_load_lds_dwordx4 v111, s[14:15]
	s_add_u32 s12, s12, 0x80
	s_addc_u32 s13, s13, 0
	s_add_u32 s14, s14, 0x80
	s_addc_u32 s15, s15, 0
	v_mfma_f32_32x32x16_bf16 v[52:67], v[84:87], v[92:95], v[52:67]
	ds_read_b128 v[150:153], v234 offset:32768
	ds_read_b128 v[154:157], v234 offset:36864
	ds_read_b128 v[158:161], v114 offset:32768
	ds_read_b128 v[162:165], v114 offset:36864
	v_mfma_f32_32x32x16_bf16 v[36:51], v[88:91], v[92:95], v[36:51]
	ds_read_b128 v[168:171], v235 offset:32768
	ds_read_b128 v[172:175], v235 offset:36864
	ds_read_b128 v[176:179], v115 offset:32768
	ds_read_b128 v[180:183], v115 offset:36864
	v_mfma_f32_32x32x16_bf16 v[20:35], v[84:87], v[96:99], v[20:35]
	ds_read_b128 v[184:187], v236 offset:32768
	ds_read_b128 v[188:191], v236 offset:36864
	ds_read_b128 v[192:195], v116 offset:32768
	ds_read_b128 v[198:201], v116 offset:36864
	v_mfma_f32_32x32x16_bf16 v[4:19], v[88:91], v[96:99], v[4:19]
	ds_read_b128 v[218:221], v237 offset:32768
	ds_read_b128 v[222:225], v237 offset:36864
	ds_read_b128 v[226:229], v117 offset:32768
	ds_read_b128 v[230:233], v117 offset:36864
	v_mfma_f32_32x32x16_bf16 v[52:67], v[118:121], v[126:129], v[52:67]
	v_mfma_f32_32x32x16_bf16 v[36:51], v[122:125], v[126:129], v[36:51]
	v_mfma_f32_32x32x16_bf16 v[20:35], v[118:121], v[130:133], v[20:35]
	v_mfma_f32_32x32x16_bf16 v[4:19], v[122:125], v[130:133], v[4:19]
	v_mfma_f32_32x32x16_bf16 v[52:67], v[134:137], v[142:145], v[52:67]
	v_mfma_f32_32x32x16_bf16 v[36:51], v[138:141], v[142:145], v[36:51]
	v_mfma_f32_32x32x16_bf16 v[20:35], v[134:137], v[146:149], v[20:35]
	v_mfma_f32_32x32x16_bf16 v[4:19], v[138:141], v[146:149], v[4:19]
	s_waitcnt vmcnt(0)
	s_waitcnt lgkmcnt(0)
	s_barrier
	v_mfma_f32_32x32x16_bf16 v[52:67], v[150:153], v[158:161], v[52:67]
	s_add_i32 m0, s100, 0x8000
	s_nop 0
	global_load_lds_dwordx4 v108, s[12:13]
	s_add_i32 m0, s100, 0x9000
	s_nop 0
	global_load_lds_dwordx4 v109, s[12:13]
	v_mfma_f32_32x32x16_bf16 v[36:51], v[154:157], v[158:161], v[36:51]
	s_add_i32 m0, s100, 0xa000
	s_nop 0
	global_load_lds_dwordx4 v110, s[12:13]
	s_add_i32 m0, s100, 0xb000
	s_nop 0
	global_load_lds_dwordx4 v111, s[12:13]
	v_mfma_f32_32x32x16_bf16 v[20:35], v[150:153], v[162:165], v[20:35]
	s_add_i32 m0, s100, 0xc000
	s_nop 0
	global_load_lds_dwordx4 v108, s[14:15]
	s_add_i32 m0, s100, 0xd000
	s_nop 0
	global_load_lds_dwordx4 v109, s[14:15]
	v_mfma_f32_32x32x16_bf16 v[4:19], v[154:157], v[162:165], v[4:19]
	s_add_i32 m0, s100, 0xe000
	s_nop 0
	global_load_lds_dwordx4 v110, s[14:15]
	s_add_i32 m0, s100, 0xf000
	s_nop 0
	global_load_lds_dwordx4 v111, s[14:15]
	s_add_u32 s12, s12, 0x80
	s_addc_u32 s13, s13, 0
	s_add_u32 s14, s14, 0x80
	s_addc_u32 s15, s15, 0
	v_mfma_f32_32x32x16_bf16 v[52:67], v[168:171], v[176:179], v[52:67]
	ds_read_b128 v[68:71], v234
	ds_read_b128 v[72:75], v234 offset:4096
	ds_read_b128 v[76:79], v114
	ds_read_b128 v[80:83], v114 offset:4096
	v_mfma_f32_32x32x16_bf16 v[36:51], v[172:175], v[176:179], v[36:51]
	ds_read_b128 v[84:87], v235
	ds_read_b128 v[88:91], v235 offset:4096
	ds_read_b128 v[92:95], v115
	ds_read_b128 v[96:99], v115 offset:4096
	v_mfma_f32_32x32x16_bf16 v[20:35], v[168:171], v[180:183], v[20:35]
	ds_read_b128 v[118:121], v236
	ds_read_b128 v[122:125], v236 offset:4096
	ds_read_b128 v[126:129], v116
	ds_read_b128 v[130:133], v116 offset:4096
	v_mfma_f32_32x32x16_bf16 v[4:19], v[172:175], v[180:183], v[4:19]
	ds_read_b128 v[134:137], v237
	ds_read_b128 v[138:141], v237 offset:4096
	ds_read_b128 v[142:145], v117
	ds_read_b128 v[146:149], v117 offset:4096
	v_mfma_f32_32x32x16_bf16 v[52:67], v[184:187], v[192:195], v[52:67]
	v_mfma_f32_32x32x16_bf16 v[36:51], v[188:191], v[192:195], v[36:51]
	v_mfma_f32_32x32x16_bf16 v[20:35], v[184:187], v[198:201], v[20:35]
	v_mfma_f32_32x32x16_bf16 v[4:19], v[188:191], v[198:201], v[4:19]
	v_mfma_f32_32x32x16_bf16 v[52:67], v[218:221], v[226:229], v[52:67]
	v_mfma_f32_32x32x16_bf16 v[36:51], v[222:225], v[226:229], v[36:51]
	v_mfma_f32_32x32x16_bf16 v[20:35], v[218:221], v[230:233], v[20:35]
	v_mfma_f32_32x32x16_bf16 v[4:19], v[222:225], v[230:233], v[4:19]
	s_add_i32 s9, s9, -1
	s_cmp_lg_u32 s9, 0
	s_cbranch_scc1 .Ldma_dn_loop
	s_waitcnt vmcnt(0)
	s_waitcnt lgkmcnt(0)
	s_barrier
; #define MFMA32(a, b, c) __builtin_amdgcn_mfma_f32_32x32x16_bf16((a), (b), (c), 0, 0, 0)
; template <int MF, int BK, class Epi>
; DI void gemm_phase_t(char* lds, const GemmDesc g, const Epi epi) {
;     ...
;       __builtin_amdgcn_sched_barrier(0);
; #pragma unroll
;       for (int kk = 0; kk < NKK; ++kk)
; #pragma unroll
;         for (int mi = 0; mi < MF; ++mi)
; #pragma unroll
;           for (int ni = 0; ni < 2; ++ni) acc[mi][ni] = MFMA32(bfr[kk][ni], af[kk][mi], acc[mi][ni]);
;     }
;     epi(acc, g.mbase + m0 + wm * (MF * 32), n0 + wn * 64, l31, h);
;   template <int MF> DI void operator()(f32x16 (&acc)[MF][2], int mb, int nb, int l31, int h) const {
; #pragma unroll
;     for (int mi = 0; mi < MF; ++mi) {
;       const int row = mb + mi * 32 + l31;
;       const float* gr = gate + (size_t)modrow(row) * 6144;
;       const float* rp = row < TL ? res_lat + (size_t)row * D : res_ctx + (size_t)(row - TL) * D;
;       float* op = row < TL ? out_lat + (size_t)row * D : out_ctx + (size_t)(row - TL) * D;
; #pragma unroll
;       for (int g4 = 0; g4 < 4; ++g4)
; #pragma unroll
;         for (int ni = 0; ni < 2; ++ni) {
;           const int col0 = nb + 16 * g4 + 8 * h + 4 * ni;
;           const float4 gt = *(const float4*)(gr + col0);
;           const float4 rv = *(const float4*)(rp + col0);
;           *(float4*)(op + col0) = make_float4(rv.x + gt.x * acc[mi][ni][4 * g4], rv.y + gt.y * acc[mi][ni][4 * g4 + 1], rv.z + gt.z * acc[mi][ni][4 * g4 + 2], rv.w + gt.w * acc[mi][ni][4 * g4 + 3]);
;         }
	v_mfma_f32_32x32x16_bf16 v[52:67], v[68:71], v[76:79], v[52:67]
	v_mfma_f32_32x32x16_bf16 v[36:51], v[72:75], v[76:79], v[36:51]
	v_mfma_f32_32x32x16_bf16 v[20:35], v[68:71], v[80:83], v[20:35]
	v_mfma_f32_32x32x16_bf16 v[4:19], v[72:75], v[80:83], v[4:19]
	v_mfma_f32_32x32x16_bf16 v[52:67], v[84:87], v[92:95], v[52:67]
	ds_read_b128 v[150:153], v234 offset:32768
	ds_read_b128 v[154:157], v234 offset:36864
	ds_read_b128 v[158:161], v114 offset:32768
	ds_read_b128 v[162:165], v114 offset:36864
	v_mfma_f32_32x32x16_bf16 v[36:51], v[88:91], v[92:95], v[36:51]
	ds_read_b128 v[168:171], v235 offset:32768
	ds_read_b128 v[172:175], v235 offset:36864
	ds_read_b128 v[176:179], v115 offset:32768
	ds_read_b128 v[180:183], v115 offset:36864
	v_mfma_f32_32x32x16_bf16 v[20:35], v[84:87], v[96:99], v[20:35]
	ds_read_b128 v[184:187], v236 offset:32768
	ds_read_b128 v[188:191], v236 offset:36864
	ds_read_b128 v[192:195], v116 offset:32768
	ds_read_b128 v[198:201], v116 offset:36864
	v_mfma_f32_32x32x16_bf16 v[4:19], v[88:91], v[96:99], v[4:19]
	ds_read_b128 v[218:221], v237 offset:32768
	ds_read_b128 v[222:225], v237 offset:36864
	ds_read_b128 v[226:229], v117 offset:32768
	ds_read_b128 v[230:233], v117 offset:36864
	v_mfma_f32_32x32x16_bf16 v[52:67], v[118:121], v[126:129], v[52:67]
	v_mfma_f32_32x32x16_bf16 v[36:51], v[122:125], v[126:129], v[36:51]
	v_mfma_f32_32x32x16_bf16 v[20:35], v[118:121], v[130:133], v[20:35]
	v_mfma_f32_32x32x16_bf16 v[4:19], v[122:125], v[130:133], v[4:19]
	v_mfma_f32_32x32x16_bf16 v[52:67], v[134:137], v[142:145], v[52:67]
	v_mfma_f32_32x32x16_bf16 v[36:51], v[138:141], v[142:145], v[36:51]
	v_mfma_f32_32x32x16_bf16 v[20:35], v[134:137], v[146:149], v[20:35]
	v_mfma_f32_32x32x16_bf16 v[4:19], v[138:141], v[146:149], v[4:19]
	s_waitcnt lgkmcnt(0)
	v_mfma_f32_32x32x16_bf16 v[52:67], v[150:153], v[158:161], v[52:67]
	v_mfma_f32_32x32x16_bf16 v[36:51], v[154:157], v[158:161], v[36:51]
	v_mfma_f32_32x32x16_bf16 v[20:35], v[150:153], v[162:165], v[20:35]
	v_mfma_f32_32x32x16_bf16 v[4:19], v[154:157], v[162:165], v[4:19]
	v_mfma_f32_32x32x16_bf16 v[52:67], v[168:171], v[176:179], v[52:67]
	v_mfma_f32_32x32x16_bf16 v[36:51], v[172:175], v[176:179], v[36:51]
	v_mfma_f32_32x32x16_bf16 v[20:35], v[168:171], v[180:183], v[20:35]
	v_mfma_f32_32x32x16_bf16 v[4:19], v[172:175], v[180:183], v[4:19]
	v_mfma_f32_32x32x16_bf16 v[52:67], v[184:187], v[192:195], v[52:67]
	v_mfma_f32_32x32x16_bf16 v[36:51], v[188:191], v[192:195], v[36:51]
	v_mfma_f32_32x32x16_bf16 v[20:35], v[184:187], v[198:201], v[20:35]
	v_mfma_f32_32x32x16_bf16 v[4:19], v[188:191], v[198:201], v[4:19]
	v_mfma_f32_32x32x16_bf16 v[52:67], v[218:221], v[226:229], v[52:67]
	v_mfma_f32_32x32x16_bf16 v[36:51], v[222:225], v[226:229], v[36:51]
	v_mfma_f32_32x32x16_bf16 v[20:35], v[218:221], v[230:233], v[20:35]
	v_mfma_f32_32x32x16_bf16 v[4:19], v[222:225], v[230:233], v[4:19]
	v_or_b32_e32 v68, s8, v113
	v_readlane_b32 s8, v252, 40
	s_add_i32 s6, s6, s8
	s_cmpk_gt_i32 s6, 0x7ff
	v_readlane_b32 s9, v252, 41
	v_mov_b32_e32 v88, s21
	v_mov_b32_e32 v89, s22
	v_mov_b32_e32 v90, s20
	v_add_u32_e32 v86, s7, v112
	v_min_i32_e32 v69, 0x8000, v86
	v_ashrrev_i32_e32 v69, 12, v69
	s_mov_b32 s7, 0x8000
	v_mul_hi_i32_i24_e32 v71, 0x6000, v69
	v_mul_i32_i24_e32 v70, 0x6000, v69
	v_cmp_gt_i32_e32 vcc, s7, v86
	v_add_u32_e32 v69, 0xffff8000, v86
	v_ashrrev_i32_e32 v72, 31, v86
	v_cndmask_b32_e32 v73, 0, v72, vcc
	v_cndmask_b32_e32 v72, v69, v86, vcc
	v_mov_b32_e32 v87, s23
	v_ashrrev_i32_e32 v69, 31, v68
	v_lshl_add_u64 v[70:71], s[2:3], 0, v[70:71]
	v_cndmask_b32_e32 v75, v87, v88, vcc
	v_cndmask_b32_e32 v74, v89, v90, vcc
	v_lshlrev_b64 v[72:73], 12, v[72:73]
	v_lshlrev_b64 v[68:69], 2, v[68:69]
	v_lshl_add_u64 v[72:73], v[74:75], 0, v[72:73]
	v_lshl_add_u64 v[84:85], v[72:73], 0, v[68:69]
	s_movk_i32 s7, 0x7fe0
	v_cmp_gt_i32_e32 vcc, s7, v86
	v_lshl_add_u64 v[82:83], v[70:71], 0, v[68:69]
	s_movk_i32 s7, 0x7fe0
	v_cmp_gt_i32_e32 vcc, s7, v86
	v_or_b32_e32 v76, 32, v86
	v_ashrrev_i32_e32 v72, 31, v76
	v_add_u32_e32 v74, 0xffff8020, v86
	v_cndmask_b32_e32 v73, 0, v72, vcc
	v_cndmask_b32_e32 v72, v74, v76, vcc
	v_cndmask_b32_e32 v75, v87, v88, vcc
	v_cndmask_b32_e32 v74, v89, v90, vcc
	v_lshlrev_b64 v[72:73], 12, v[72:73]
	v_lshl_add_u64 v[72:73], v[74:75], 0, v[72:73]
	v_lshl_add_u64 v[80:81], v[72:73], 0, v[68:69]
	global_load_dwordx4 v[118:121], v[82:83], off
	global_load_dwordx4 v[150:153], v[84:85], off
	global_load_dwordx4 v[122:125], v[82:83], off offset:16
	global_load_dwordx4 v[154:157], v[84:85], off offset:16
	global_load_dwordx4 v[126:129], v[82:83], off offset:64
	global_load_dwordx4 v[158:161], v[84:85], off offset:64
	global_load_dwordx4 v[130:133], v[82:83], off offset:80
	global_load_dwordx4 v[162:165], v[84:85], off offset:80
	global_load_dwordx4 v[134:137], v[82:83], off offset:128
	global_load_dwordx4 v[168:171], v[84:85], off offset:128
	global_load_dwordx4 v[138:141], v[82:83], off offset:144
	global_load_dwordx4 v[172:175], v[84:85], off offset:144
	global_load_dwordx4 v[142:145], v[82:83], off offset:192
	global_load_dwordx4 v[176:179], v[84:85], off offset:192
	global_load_dwordx4 v[146:149], v[82:83], off offset:208
	global_load_dwordx4 v[180:183], v[84:85], off offset:208
	global_load_dwordx4 v[184:187], v[80:81], off
	global_load_dwordx4 v[188:191], v[80:81], off offset:16
	global_load_dwordx4 v[192:195], v[80:81], off offset:64
	global_load_dwordx4 v[198:201], v[80:81], off offset:80
	global_load_dwordx4 v[218:221], v[80:81], off offset:128
	global_load_dwordx4 v[222:225], v[80:81], off offset:144
	global_load_dwordx4 v[226:229], v[80:81], off offset:192
	global_load_dwordx4 v[230:233], v[80:81], off offset:208
	s_waitcnt vmcnt(8)
;   template <int MF> DI void operator()(f32x16 (&acc)[MF][2], int mb, int nb, int l31, int h) const {
;     ...
;       for (int g4 = 0; g4 < 4; ++g4)
; #pragma unroll
;         for (int ni = 0; ni < 2; ++ni) {
;           const int col0 = nb + 16 * g4 + 8 * h + 4 * ni;
;           const float4 gt = *(const float4*)(gr + col0);
;           const float4 rv = *(const float4*)(rp + col0);
;           *(float4*)(op + col0) = make_float4(rv.x + gt.x * acc[mi][ni][4 * g4], rv.y + gt.y * acc[mi][ni][4 * g4 + 1], rv.z + gt.z * acc[mi][ni][4 * g4 + 2], rv.w + gt.w * acc[mi][ni][4 * g4 + 3]);
;         }
	s_nop 4
	v_fma_f32 v52, v52, v118, v150
	v_fma_f32 v53, v53, v119, v151
	v_fma_f32 v54, v54, v120, v152
	v_fma_f32 v55, v55, v121, v153
	global_store_dwordx4 v[84:85], v[52:55], off
	v_fma_f32 v36, v36, v122, v154
	v_fma_f32 v37, v37, v123, v155
	v_fma_f32 v38, v38, v124, v156
	v_fma_f32 v39, v39, v125, v157
	global_store_dwordx4 v[84:85], v[36:39], off offset:16
	v_fma_f32 v56, v56, v126, v158
	v_fma_f32 v57, v57, v127, v159
	v_fma_f32 v58, v58, v128, v160
	v_fma_f32 v59, v59, v129, v161
	global_store_dwordx4 v[84:85], v[56:59], off offset:64
	v_fma_f32 v40, v40, v130, v162
	v_fma_f32 v41, v41, v131, v163
	v_fma_f32 v42, v42, v132, v164
	v_fma_f32 v43, v43, v133, v165
	global_store_dwordx4 v[84:85], v[40:43], off offset:80
	v_fma_f32 v60, v60, v134, v168
	v_fma_f32 v61, v61, v135, v169
	v_fma_f32 v62, v62, v136, v170
	v_fma_f32 v63, v63, v137, v171
	global_store_dwordx4 v[84:85], v[60:63], off offset:128
	v_fma_f32 v44, v44, v138, v172
	v_fma_f32 v45, v45, v139, v173
	v_fma_f32 v46, v46, v140, v174
	v_fma_f32 v47, v47, v141, v175
	global_store_dwordx4 v[84:85], v[44:47], off offset:144
	v_fma_f32 v64, v64, v142, v176
	v_fma_f32 v65, v65, v143, v177
	v_fma_f32 v66, v66, v144, v178
	v_fma_f32 v67, v67, v145, v179
	global_store_dwordx4 v[84:85], v[64:67], off offset:192
	v_fma_f32 v48, v48, v146, v180
	v_fma_f32 v49, v49, v147, v181
	v_fma_f32 v50, v50, v148, v182
	v_fma_f32 v51, v51, v149, v183
	global_store_dwordx4 v[84:85], v[48:51], off offset:208
	s_waitcnt vmcnt(8)
	v_fma_f32 v20, v20, v118, v184
	v_fma_f32 v21, v21, v119, v185
	v_fma_f32 v22, v22, v120, v186
	v_fma_f32 v23, v23, v121, v187
	global_store_dwordx4 v[80:81], v[20:23], off
	v_fma_f32 v4, v4, v122, v188
	v_fma_f32 v5, v5, v123, v189
	v_fma_f32 v6, v6, v124, v190
	v_fma_f32 v7, v7, v125, v191
	global_store_dwordx4 v[80:81], v[4:7], off offset:16
	v_fma_f32 v24, v24, v126, v192
	v_fma_f32 v25, v25, v127, v193
	v_fma_f32 v26, v26, v128, v194
	v_fma_f32 v27, v27, v129, v195
	global_store_dwordx4 v[80:81], v[24:27], off offset:64
	v_fma_f32 v8, v8, v130, v198
	v_fma_f32 v9, v9, v131, v199
	v_fma_f32 v10, v10, v132, v200
	v_fma_f32 v11, v11, v133, v201
	global_store_dwordx4 v[80:81], v[8:11], off offset:80
	v_fma_f32 v28, v28, v134, v218
	v_fma_f32 v29, v29, v135, v219
	v_fma_f32 v30, v30, v136, v220
	v_fma_f32 v31, v31, v137, v221
	global_store_dwordx4 v[80:81], v[28:31], off offset:128
	v_fma_f32 v12, v12, v138, v222
	v_fma_f32 v13, v13, v139, v223
	v_fma_f32 v14, v14, v140, v224
	v_fma_f32 v15, v15, v141, v225
	global_store_dwordx4 v[80:81], v[12:15], off offset:144
	v_fma_f32 v32, v32, v142, v226
	v_fma_f32 v33, v33, v143, v227
	v_fma_f32 v34, v34, v144, v228
	v_fma_f32 v35, v35, v145, v229
	global_store_dwordx4 v[80:81], v[32:35], off offset:192
	v_fma_f32 v16, v16, v146, v230
	v_fma_f32 v17, v17, v147, v231
	v_fma_f32 v18, v18, v148, v232
	v_fma_f32 v19, v19, v149, v233
	global_store_dwordx4 v[80:81], v[16:19], off offset:208
	s_cbranch_scc0 .LBB0_34

; #define MFMA32(a, b, c) __builtin_amdgcn_mfma_f32_32x32x16_bf16((a), (b), (c), 0, 0, 0)
; template <int MF, int BK, class Epi>
; DI void gemm_phase_t(char* lds, const GemmDesc g, const Epi epi) {
;     ...
;     for (int kt = 0; kt < nk; ++kt) {
;       __syncthreads();
;       const u16* sA = sbase + (kt & 1) * STG;
;       const u16* sB = sA + BM * LS;
;       if (kt + 1 < nk) {
;         u16* nA = sbase + ((kt + 1) & 1) * STG;
; #pragma unroll
;         for (int j = 0; j < APT; ++j) *(u32x4*)(nA + (lr + RSTEP * j) * LS + lc * 8) = ra[j];
; #pragma unroll
;         for (int j = 0; j < BPT; ++j) *(u32x4*)(nA + BM * LS + (lr + RSTEP * j) * LS + lc * 8) = rb[j];
;         if (kt + 2 < nk) {
; #pragma unroll
;           for (int j = 0; j < APT; ++j) ra[j] = *(const u32x4*)(Ap + (size_t)j * RSTEP * g.lda + (kt + 2) * BK);
; #pragma unroll
;           for (int j = 0; j < BPT; ++j) rb[j] = *(const u32x4*)(Bp + (size_t)j * RSTEP * g.ldb + (kt + 2) * BK);
;         }
;       }
;       bf16x8 af[NKK][MF], bfr[NKK][2];
; #pragma unroll
;       for (int kk = 0; kk < NKK; ++kk) {
; #pragma unroll
;         for (int ni = 0; ni < 2; ++ni) bfr[kk][ni] = *(const bf16x8*)(sB + (wn * 64 + ni * 32 + l31) * LS + kk * 16 + h * 8);
; #pragma unroll
;         for (int mi = 0; mi < MF; ++mi) af[kk][mi] = *(const bf16x8*)(sA + (wm * (MF * 32) + mi * 32 + l31) * LS + kk * 16 + h * 8);
;       }
;       __builtin_amdgcn_sched_barrier(0);
; #pragma unroll
;       for (int kk = 0; kk < NKK; ++kk)
; #pragma unroll
;         for (int mi = 0; mi < MF; ++mi)
; #pragma unroll
;           for (int ni = 0; ni < 2; ++ni) acc[mi][ni] = MFMA32(bfr[kk][ni], af[kk][mi], acc[mi][ni]);
;     }
.Ldma_op_loop:
	s_waitcnt vmcnt(0)
	s_waitcnt lgkmcnt(0)
	s_barrier
	v_mfma_f32_32x32x16_bf16 v[52:67], v[68:71], v[76:79], v[52:67]
	s_add_i32 m0, s100, 0x0
	s_nop 0
	global_load_lds_dwordx4 v108, s[12:13]
	s_add_i32 m0, s100, 0x1000
	s_nop 0
	global_load_lds_dwordx4 v109, s[12:13]
	v_mfma_f32_32x32x16_bf16 v[36:51], v[72:75], v[76:79], v[36:51]
	s_add_i32 m0, s100, 0x2000
	s_nop 0
	global_load_lds_dwordx4 v110, s[12:13]
	s_add_i32 m0, s100, 0x3000
	s_nop 0
	global_load_lds_dwordx4 v111, s[12:13]
	v_mfma_f32_32x32x16_bf16 v[20:35], v[68:71], v[80:83], v[20:35]
	s_add_i32 m0, s100, 0x4000
	s_nop 0
	global_load_lds_dwordx4 v108, s[14:15]
	s_add_i32 m0, s100, 0x5000
	s_nop 0
	global_load_lds_dwordx4 v109, s[14:15]
	v_mfma_f32_32x32x16_bf16 v[4:19], v[72:75], v[80:83], v[4:19]
	s_add_i32 m0, s100, 0x6000
	s_nop 0
	global_load_lds_dwordx4 v110, s[14:15]
	s_add_i32 m0, s100, 0x7000
	s_nop 0
	global_load_lds_dwordx4 v111, s[14:15]
	s_add_u32 s12, s12, 0x80
	s_addc_u32 s13, s13, 0
	s_add_u32 s14, s14, 0x80
	s_addc_u32 s15, s15, 0
	v_mfma_f32_32x32x16_bf16 v[52:67], v[84:87], v[92:95], v[52:67]
	ds_read_b128 v[150:153], v234 offset:32768
	ds_read_b128 v[154:157], v234 offset:36864
	ds_read_b128 v[158:161], v238 offset:32768
	ds_read_b128 v[162:165], v238 offset:36864
	v_mfma_f32_32x32x16_bf16 v[36:51], v[88:91], v[92:95], v[36:51]
	ds_read_b128 v[168:171], v235 offset:32768
	ds_read_b128 v[172:175], v235 offset:36864
	ds_read_b128 v[176:179], v239 offset:32768
	ds_read_b128 v[180:183], v239 offset:36864
	v_mfma_f32_32x32x16_bf16 v[20:35], v[84:87], v[96:99], v[20:35]
	ds_read_b128 v[184:187], v236 offset:32768
	ds_read_b128 v[188:191], v236 offset:36864
	ds_read_b128 v[192:195], v240 offset:32768
	ds_read_b128 v[198:201], v240 offset:36864
	v_mfma_f32_32x32x16_bf16 v[4:19], v[88:91], v[96:99], v[4:19]
	ds_read_b128 v[218:221], v237 offset:32768
	ds_read_b128 v[222:225], v237 offset:36864
	ds_read_b128 v[226:229], v241 offset:32768
	ds_read_b128 v[230:233], v241 offset:36864
	v_mfma_f32_32x32x16_bf16 v[52:67], v[118:121], v[126:129], v[52:67]
	v_mfma_f32_32x32x16_bf16 v[36:51], v[122:125], v[126:129], v[36:51]
	v_mfma_f32_32x32x16_bf16 v[20:35], v[118:121], v[130:133], v[20:35]
	v_mfma_f32_32x32x16_bf16 v[4:19], v[122:125], v[130:133], v[4:19]
	v_mfma_f32_32x32x16_bf16 v[52:67], v[134:137], v[142:145], v[52:67]
	v_mfma_f32_32x32x16_bf16 v[36:51], v[138:141], v[142:145], v[36:51]
	v_mfma_f32_32x32x16_bf16 v[20:35], v[134:137], v[146:149], v[20:35]
	v_mfma_f32_32x32x16_bf16 v[4:19], v[138:141], v[146:149], v[4:19]
	s_waitcnt vmcnt(0)
	s_waitcnt lgkmcnt(0)
	s_barrier
	v_mfma_f32_32x32x16_bf16 v[52:67], v[150:153], v[158:161], v[52:67]
	s_add_i32 m0, s100, 0x8000
	s_nop 0
	global_load_lds_dwordx4 v108, s[12:13]
	s_add_i32 m0, s100, 0x9000
	s_nop 0
	global_load_lds_dwordx4 v109, s[12:13]
	v_mfma_f32_32x32x16_bf16 v[36:51], v[154:157], v[158:161], v[36:51]
	s_add_i32 m0, s100, 0xa000
	s_nop 0
	global_load_lds_dwordx4 v110, s[12:13]
	s_add_i32 m0, s100, 0xb000
	s_nop 0
	global_load_lds_dwordx4 v111, s[12:13]
	v_mfma_f32_32x32x16_bf16 v[20:35], v[150:153], v[162:165], v[20:35]
	s_add_i32 m0, s100, 0xc000
	s_nop 0
	global_load_lds_dwordx4 v108, s[14:15]
	s_add_i32 m0, s100, 0xd000
	s_nop 0
	global_load_lds_dwordx4 v109, s[14:15]
	v_mfma_f32_32x32x16_bf16 v[4:19], v[154:157], v[162:165], v[4:19]
	s_add_i32 m0, s100, 0xe000
	s_nop 0
	global_load_lds_dwordx4 v110, s[14:15]
	s_add_i32 m0, s100, 0xf000
	s_nop 0
	global_load_lds_dwordx4 v111, s[14:15]
	s_add_u32 s12, s12, 0x80
	s_addc_u32 s13, s13, 0
	s_add_u32 s14, s14, 0x80
	s_addc_u32 s15, s15, 0
	v_mfma_f32_32x32x16_bf16 v[52:67], v[168:171], v[176:179], v[52:67]
	ds_read_b128 v[68:71], v234
	ds_read_b128 v[72:75], v234 offset:4096
	ds_read_b128 v[76:79], v238
	ds_read_b128 v[80:83], v238 offset:4096
	v_mfma_f32_32x32x16_bf16 v[36:51], v[172:175], v[176:179], v[36:51]
	ds_read_b128 v[84:87], v235
	ds_read_b128 v[88:91], v235 offset:4096
	ds_read_b128 v[92:95], v239
	ds_read_b128 v[96:99], v239 offset:4096
	v_mfma_f32_32x32x16_bf16 v[20:35], v[168:171], v[180:183], v[20:35]
	ds_read_b128 v[118:121], v236
	ds_read_b128 v[122:125], v236 offset:4096
	ds_read_b128 v[126:129], v240
	ds_read_b128 v[130:133], v240 offset:4096
	v_mfma_f32_32x32x16_bf16 v[4:19], v[172:175], v[180:183], v[4:19]
	ds_read_b128 v[134:137], v237
	ds_read_b128 v[138:141], v237 offset:4096
	ds_read_b128 v[142:145], v241
	ds_read_b128 v[146:149], v241 offset:4096
	v_mfma_f32_32x32x16_bf16 v[52:67], v[184:187], v[192:195], v[52:67]
	v_mfma_f32_32x32x16_bf16 v[36:51], v[188:191], v[192:195], v[36:51]
	v_mfma_f32_32x32x16_bf16 v[20:35], v[184:187], v[198:201], v[20:35]
	v_mfma_f32_32x32x16_bf16 v[4:19], v[188:191], v[198:201], v[4:19]
	v_mfma_f32_32x32x16_bf16 v[52:67], v[218:221], v[226:229], v[52:67]
	v_mfma_f32_32x32x16_bf16 v[36:51], v[222:225], v[226:229], v[36:51]
	v_mfma_f32_32x32x16_bf16 v[20:35], v[218:221], v[230:233], v[20:35]
	v_mfma_f32_32x32x16_bf16 v[4:19], v[222:225], v[230:233], v[4:19]
	s_add_i32 s9, s9, -1
	s_cmp_lg_u32 s9, 0
	s_cbranch_scc1 .Ldma_op_loop
	s_waitcnt vmcnt(0)
	s_waitcnt lgkmcnt(0)
	s_barrier
; #define MFMA32(a, b, c) __builtin_amdgcn_mfma_f32_32x32x16_bf16((a), (b), (c), 0, 0, 0)
; template <int MF, int BK, class Epi>
; DI void gemm_phase_t(char* lds, const GemmDesc g, const Epi epi) {
;     ...
;       __builtin_amdgcn_sched_barrier(0);
; #pragma unroll
;       for (int kk = 0; kk < NKK; ++kk)
; #pragma unroll
;         for (int mi = 0; mi < MF; ++mi)
; #pragma unroll
;           for (int ni = 0; ni < 2; ++ni) acc[mi][ni] = MFMA32(bfr[kk][ni], af[kk][mi], acc[mi][ni]);
;     }
;     epi(acc, g.mbase + m0 + wm * (MF * 32), n0 + wn * 64, l31, h);
;   template <int MF> DI void operator()(f32x16 (&acc)[MF][2], int mb, int nb, int l31, int h) const {
; #pragma unroll
;     for (int mi = 0; mi < MF; ++mi) {
;       const int row = mb + mi * 32 + l31;
;       const float* gr = gate + (size_t)modrow(row) * 6144;
;       const float* rp = row < TL ? res_lat + (size_t)row * D : res_ctx + (size_t)(row - TL) * D;
;       float* op = row < TL ? out_lat + (size_t)row * D : out_ctx + (size_t)(row - TL) * D;
; #pragma unroll
;       for (int g4 = 0; g4 < 4; ++g4)
; #pragma unroll
;         for (int ni = 0; ni < 2; ++ni) {
;           const int col0 = nb + 16 * g4 + 8 * h + 4 * ni;
;           const float4 gt = *(const float4*)(gr + col0);
;           const float4 rv = *(const float4*)(rp + col0);
;           *(float4*)(op + col0) = make_float4(rv.x + gt.x * acc[mi][ni][4 * g4], rv.y + gt.y * acc[mi][ni][4 * g4 + 1], rv.z + gt.z * acc[mi][ni][4 * g4 + 2], rv.w + gt.w * acc[mi][ni][4 * g4 + 3]);
;         }
	v_mfma_f32_32x32x16_bf16 v[52:67], v[68:71], v[76:79], v[52:67]
	v_mfma_f32_32x32x16_bf16 v[36:51], v[72:75], v[76:79], v[36:51]
	v_mfma_f32_32x32x16_bf16 v[20:35], v[68:71], v[80:83], v[20:35]
	v_mfma_f32_32x32x16_bf16 v[4:19], v[72:75], v[80:83], v[4:19]
	v_mfma_f32_32x32x16_bf16 v[52:67], v[84:87], v[92:95], v[52:67]
	ds_read_b128 v[150:153], v234 offset:32768
	ds_read_b128 v[154:157], v234 offset:36864
	ds_read_b128 v[158:161], v238 offset:32768
	ds_read_b128 v[162:165], v238 offset:36864
	v_mfma_f32_32x32x16_bf16 v[36:51], v[88:91], v[92:95], v[36:51]
	ds_read_b128 v[168:171], v235 offset:32768
	ds_read_b128 v[172:175], v235 offset:36864
	ds_read_b128 v[176:179], v239 offset:32768
	ds_read_b128 v[180:183], v239 offset:36864
	v_mfma_f32_32x32x16_bf16 v[20:35], v[84:87], v[96:99], v[20:35]
	ds_read_b128 v[184:187], v236 offset:32768
	ds_read_b128 v[188:191], v236 offset:36864
	ds_read_b128 v[192:195], v240 offset:32768
	ds_read_b128 v[198:201], v240 offset:36864
	v_mfma_f32_32x32x16_bf16 v[4:19], v[88:91], v[96:99], v[4:19]
	ds_read_b128 v[218:221], v237 offset:32768
	ds_read_b128 v[222:225], v237 offset:36864
	ds_read_b128 v[226:229], v241 offset:32768
	ds_read_b128 v[230:233], v241 offset:36864
	v_mfma_f32_32x32x16_bf16 v[52:67], v[118:121], v[126:129], v[52:67]
	v_mfma_f32_32x32x16_bf16 v[36:51], v[122:125], v[126:129], v[36:51]
	v_mfma_f32_32x32x16_bf16 v[20:35], v[118:121], v[130:133], v[20:35]
	v_mfma_f32_32x32x16_bf16 v[4:19], v[122:125], v[130:133], v[4:19]
	v_mfma_f32_32x32x16_bf16 v[52:67], v[134:137], v[142:145], v[52:67]
	v_mfma_f32_32x32x16_bf16 v[36:51], v[138:141], v[142:145], v[36:51]
	v_mfma_f32_32x32x16_bf16 v[20:35], v[134:137], v[146:149], v[20:35]
	v_mfma_f32_32x32x16_bf16 v[4:19], v[138:141], v[146:149], v[4:19]
	s_waitcnt lgkmcnt(0)
	v_mfma_f32_32x32x16_bf16 v[52:67], v[150:153], v[158:161], v[52:67]
	v_mfma_f32_32x32x16_bf16 v[36:51], v[154:157], v[158:161], v[36:51]
	v_mfma_f32_32x32x16_bf16 v[20:35], v[150:153], v[162:165], v[20:35]
	v_mfma_f32_32x32x16_bf16 v[4:19], v[154:157], v[162:165], v[4:19]
	v_mfma_f32_32x32x16_bf16 v[52:67], v[168:171], v[176:179], v[52:67]
	v_mfma_f32_32x32x16_bf16 v[36:51], v[172:175], v[176:179], v[36:51]
	v_mfma_f32_32x32x16_bf16 v[20:35], v[168:171], v[180:183], v[20:35]
	v_mfma_f32_32x32x16_bf16 v[4:19], v[172:175], v[180:183], v[4:19]
	v_mfma_f32_32x32x16_bf16 v[52:67], v[184:187], v[192:195], v[52:67]
	v_mfma_f32_32x32x16_bf16 v[36:51], v[188:191], v[192:195], v[36:51]
	v_mfma_f32_32x32x16_bf16 v[20:35], v[184:187], v[198:201], v[20:35]
	v_mfma_f32_32x32x16_bf16 v[4:19], v[188:191], v[198:201], v[4:19]
	v_mfma_f32_32x32x16_bf16 v[52:67], v[218:221], v[226:229], v[52:67]
	v_mfma_f32_32x32x16_bf16 v[36:51], v[222:225], v[226:229], v[36:51]
	v_mfma_f32_32x32x16_bf16 v[20:35], v[218:221], v[230:233], v[20:35]
	v_mfma_f32_32x32x16_bf16 v[4:19], v[222:225], v[230:233], v[4:19]
	v_readlane_b32 s10, v253, 26
	v_readlane_b32 s11, v253, 27
	v_or_b32_e32 v68, s7, v114
	v_mov_b32_e32 v88, s10
	v_mov_b32_e32 v89, s31
	v_mov_b32_e32 v90, s29
	v_mov_b32_e32 v91, s30
	v_add_u32_e32 v84, s6, v113
	v_min_i32_e32 v69, 0x8000, v84
	s_mov_b32 s6, 0x8000
	v_ashrrev_i32_e32 v69, 12, v69
	v_cmp_gt_i32_e32 vcc, s6, v84
	v_readlane_b32 s6, v253, 28
	v_mul_hi_i32_i24_e32 v71, 0x6000, v69
	v_mul_i32_i24_e32 v70, 0x6000, v69
	v_add_u32_e32 v69, 0xffff8000, v84
	v_ashrrev_i32_e32 v72, 31, v84
	v_readlane_b32 s7, v253, 29
	v_cndmask_b32_e32 v73, 0, v72, vcc
	v_cndmask_b32_e32 v72, v69, v84, vcc
	v_mov_b32_e32 v85, s7
	v_mov_b32_e32 v86, s11
	v_mov_b32_e32 v87, s6
	v_mov_b32_e32 v92, s28
	v_ashrrev_i32_e32 v69, 31, v68
	v_lshl_add_u64 v[70:71], s[0:1], 0, v[70:71]
	v_cndmask_b32_e32 v75, v85, v86, vcc
	v_cndmask_b32_e32 v74, v87, v88, vcc
	v_lshlrev_b64 v[72:73], 12, v[72:73]
	v_cndmask_b32_e32 v77, v89, v90, vcc
	v_cndmask_b32_e32 v76, v91, v92, vcc
	v_lshlrev_b64 v[68:69], 2, v[68:69]
	v_lshl_add_u64 v[74:75], v[74:75], 0, v[72:73]
	v_lshl_add_u64 v[72:73], v[76:77], 0, v[72:73]
	v_lshl_add_u64 v[78:79], v[70:71], 0, v[68:69]
	v_lshl_add_u64 v[80:81], v[74:75], 0, v[68:69]
	v_lshl_add_u64 v[82:83], v[72:73], 0, v[68:69]
	s_movk_i32 s6, 0x7fe0
	v_cmp_gt_i32_e32 vcc, s6, v84
	v_readlane_b32 s6, v252, 40
	s_add_i32 s8, s8, s6
	s_cmpk_gt_i32 s8, 0x7ff
	v_readlane_b32 s7, v252, 41
	v_or_b32_e32 v76, 32, v84
	v_cndmask_b32_e32 v75, v89, v90, vcc
	v_cndmask_b32_e32 v74, v91, v92, vcc
	v_ashrrev_i32_e32 v70, 31, v76
	v_add_u32_e32 v72, 0xffff8020, v84
	v_cndmask_b32_e32 v71, 0, v70, vcc
	v_cndmask_b32_e32 v70, v72, v76, vcc
	v_cndmask_b32_e32 v73, v85, v86, vcc
	v_cndmask_b32_e32 v72, v87, v88, vcc
	v_lshlrev_b64 v[70:71], 12, v[70:71]
	v_lshl_add_u64 v[72:73], v[72:73], 0, v[70:71]
	v_lshl_add_u64 v[70:71], v[74:75], 0, v[70:71]
	v_lshl_add_u64 v[96:97], v[72:73], 0, v[68:69]
	v_lshl_add_u64 v[98:99], v[70:71], 0, v[68:69]
	global_load_dwordx4 v[118:121], v[78:79], off
	global_load_dwordx4 v[150:153], v[80:81], off
	global_load_dwordx4 v[122:125], v[78:79], off offset:16
	global_load_dwordx4 v[154:157], v[80:81], off offset:16
	global_load_dwordx4 v[126:129], v[78:79], off offset:64
	global_load_dwordx4 v[158:161], v[80:81], off offset:64
	global_load_dwordx4 v[130:133], v[78:79], off offset:80
	global_load_dwordx4 v[162:165], v[80:81], off offset:80
	global_load_dwordx4 v[134:137], v[78:79], off offset:128
	global_load_dwordx4 v[168:171], v[80:81], off offset:128
	global_load_dwordx4 v[138:141], v[78:79], off offset:144
	global_load_dwordx4 v[172:175], v[80:81], off offset:144
	global_load_dwordx4 v[142:145], v[78:79], off offset:192
	global_load_dwordx4 v[176:179], v[80:81], off offset:192
	global_load_dwordx4 v[146:149], v[78:79], off offset:208
	global_load_dwordx4 v[180:183], v[80:81], off offset:208
	global_load_dwordx4 v[184:187], v[96:97], off
	global_load_dwordx4 v[188:191], v[96:97], off offset:16
	global_load_dwordx4 v[192:195], v[96:97], off offset:64
	global_load_dwordx4 v[198:201], v[96:97], off offset:80
	global_load_dwordx4 v[218:221], v[96:97], off offset:128
	global_load_dwordx4 v[222:225], v[96:97], off offset:144
	global_load_dwordx4 v[226:229], v[96:97], off offset:192
	global_load_dwordx4 v[230:233], v[96:97], off offset:208
	s_waitcnt vmcnt(8)
;   template <int MF> DI void operator()(f32x16 (&acc)[MF][2], int mb, int nb, int l31, int h) const {
;     ...
;       for (int g4 = 0; g4 < 4; ++g4)
; #pragma unroll
;         for (int ni = 0; ni < 2; ++ni) {
;           const int col0 = nb + 16 * g4 + 8 * h + 4 * ni;
;           const float4 gt = *(const float4*)(gr + col0);
;           const float4 rv = *(const float4*)(rp + col0);
;           *(float4*)(op + col0) = make_float4(rv.x + gt.x * acc[mi][ni][4 * g4], rv.y + gt.y * acc[mi][ni][4 * g4 + 1], rv.z + gt.z * acc[mi][ni][4 * g4 + 2], rv.w + gt.w * acc[mi][ni][4 * g4 + 3]);
;         }
	s_nop 4
	v_fma_f32 v52, v52, v118, v150
	v_fma_f32 v53, v53, v119, v151
	v_fma_f32 v54, v54, v120, v152
	v_fma_f32 v55, v55, v121, v153
	global_store_dwordx4 v[82:83], v[52:55], off
	v_fma_f32 v36, v36, v122, v154
	v_fma_f32 v37, v37, v123, v155
	v_fma_f32 v38, v38, v124, v156
	v_fma_f32 v39, v39, v125, v157
	global_store_dwordx4 v[82:83], v[36:39], off offset:16
	v_fma_f32 v56, v56, v126, v158
	v_fma_f32 v57, v57, v127, v159
	v_fma_f32 v58, v58, v128, v160
	v_fma_f32 v59, v59, v129, v161
	global_store_dwordx4 v[82:83], v[56:59], off offset:64
	v_fma_f32 v40, v40, v130, v162
	v_fma_f32 v41, v41, v131, v163
	v_fma_f32 v42, v42, v132, v164
	v_fma_f32 v43, v43, v133, v165
	global_store_dwordx4 v[82:83], v[40:43], off offset:80
	v_fma_f32 v60, v60, v134, v168
	v_fma_f32 v61, v61, v135, v169
	v_fma_f32 v62, v62, v136, v170
	v_fma_f32 v63, v63, v137, v171
	global_store_dwordx4 v[82:83], v[60:63], off offset:128
	v_fma_f32 v44, v44, v138, v172
	v_fma_f32 v45, v45, v139, v173
	v_fma_f32 v46, v46, v140, v174
	v_fma_f32 v47, v47, v141, v175
	global_store_dwordx4 v[82:83], v[44:47], off offset:144
	v_fma_f32 v64, v64, v142, v176
	v_fma_f32 v65, v65, v143, v177
	v_fma_f32 v66, v66, v144, v178
	v_fma_f32 v67, v67, v145, v179
	global_store_dwordx4 v[82:83], v[64:67], off offset:192
	v_fma_f32 v48, v48, v146, v180
	v_fma_f32 v49, v49, v147, v181
	v_fma_f32 v50, v50, v148, v182
	v_fma_f32 v51, v51, v149, v183
	global_store_dwordx4 v[82:83], v[48:51], off offset:208
	s_waitcnt vmcnt(8)
	v_fma_f32 v20, v20, v118, v184
	v_fma_f32 v21, v21, v119, v185
	v_fma_f32 v22, v22, v120, v186
	v_fma_f32 v23, v23, v121, v187
	global_store_dwordx4 v[98:99], v[20:23], off
	v_fma_f32 v4, v4, v122, v188
	v_fma_f32 v5, v5, v123, v189
	v_fma_f32 v6, v6, v124, v190
	v_fma_f32 v7, v7, v125, v191
	global_store_dwordx4 v[98:99], v[4:7], off offset:16
	v_fma_f32 v24, v24, v126, v192
	v_fma_f32 v25, v25, v127, v193
	v_fma_f32 v26, v26, v128, v194
	v_fma_f32 v27, v27, v129, v195
	global_store_dwordx4 v[98:99], v[24:27], off offset:64
	v_fma_f32 v8, v8, v130, v198
	v_fma_f32 v9, v9, v131, v199
	v_fma_f32 v10, v10, v132, v200
	v_fma_f32 v11, v11, v133, v201
	global_store_dwordx4 v[98:99], v[8:11], off offset:80
	v_fma_f32 v28, v28, v134, v218
	v_fma_f32 v29, v29, v135, v219
	v_fma_f32 v30, v30, v136, v220
	v_fma_f32 v31, v31, v137, v221
	global_store_dwordx4 v[98:99], v[28:31], off offset:128
	v_fma_f32 v12, v12, v138, v222
	v_fma_f32 v13, v13, v139, v223
	v_fma_f32 v14, v14, v140, v224
	v_fma_f32 v15, v15, v141, v225
	global_store_dwordx4 v[98:99], v[12:15], off offset:144
	v_fma_f32 v32, v32, v142, v226
	v_fma_f32 v33, v33, v143, v227
	v_fma_f32 v34, v34, v144, v228
	v_fma_f32 v35, v35, v145, v229
	global_store_dwordx4 v[98:99], v[32:35], off offset:192
	v_fma_f32 v16, v16, v146, v230
	v_fma_f32 v17, v17, v147, v231
	v_fma_f32 v18, v18, v148, v232
	v_fma_f32 v19, v19, v149, v233
	global_store_dwordx4 v[98:99], v[16:19], off offset:208
	s_cbranch_scc0 .LBB0_305

; #define MFMA32(a, b, c) __builtin_amdgcn_mfma_f32_32x32x16_bf16((a), (b), (c), 0, 0, 0)
; template <int MF, int BK, class Epi>
; DI void gemm_phase_t(char* lds, const GemmDesc g, const Epi epi) {
;     ...
;     for (int kt = 0; kt < nk; ++kt) {
;       __syncthreads();
;       const u16* sA = sbase + (kt & 1) * STG;
;       const u16* sB = sA + BM * LS;
;       if (kt + 1 < nk) {
;         u16* nA = sbase + ((kt + 1) & 1) * STG;
; #pragma unroll
;         for (int j = 0; j < APT; ++j) *(u32x4*)(nA + (lr + RSTEP * j) * LS + lc * 8) = ra[j];
; #pragma unroll
;         for (int j = 0; j < BPT; ++j) *(u32x4*)(nA + BM * LS + (lr + RSTEP * j) * LS + lc * 8) = rb[j];
;         if (kt + 2 < nk) {
; #pragma unroll
;           for (int j = 0; j < APT; ++j) ra[j] = *(const u32x4*)(Ap + (size_t)j * RSTEP * g.lda + (kt + 2) * BK);
; #pragma unroll
;           for (int j = 0; j < BPT; ++j) rb[j] = *(const u32x4*)(Bp + (size_t)j * RSTEP * g.ldb + (kt + 2) * BK);
;         }
;       }
;       bf16x8 af[NKK][MF], bfr[NKK][2];
; #pragma unroll
;       for (int kk = 0; kk < NKK; ++kk) {
; #pragma unroll
;         for (int ni = 0; ni < 2; ++ni) bfr[kk][ni] = *(const bf16x8*)(sB + (wn * 64 + ni * 32 + l31) * LS + kk * 16 + h * 8);
; #pragma unroll
;         for (int mi = 0; mi < MF; ++mi) af[kk][mi] = *(const bf16x8*)(sA + (wm * (MF * 32) + mi * 32 + l31) * LS + kk * 16 + h * 8);
;       }
;       __builtin_amdgcn_sched_barrier(0);
; #pragma unroll
;       for (int kk = 0; kk < NKK; ++kk)
; #pragma unroll
;         for (int mi = 0; mi < MF; ++mi)
; #pragma unroll
;           for (int ni = 0; ni < 2; ++ni) acc[mi][ni] = MFMA32(bfr[kk][ni], af[kk][mi], acc[mi][ni]);
;     }
.Ldma_oi_loop:
	s_waitcnt vmcnt(0)
	s_waitcnt lgkmcnt(0)
	s_barrier
	v_mfma_f32_32x32x16_bf16 v[52:67], v[102:105], v[110:113], v[52:67]
	s_add_i32 m0, s3, 0x0
	s_nop 0
	global_load_lds_dwordx4 v68, s[98:99]
	s_add_i32 m0, s3, 0x1000
	s_nop 0
	global_load_lds_dwordx4 v69, s[98:99]
	v_mfma_f32_32x32x16_bf16 v[36:51], v[106:109], v[110:113], v[36:51]
	s_add_i32 m0, s3, 0x2000
	s_nop 0
	global_load_lds_dwordx4 v70, s[98:99]
	s_add_i32 m0, s3, 0x3000
	s_nop 0
	global_load_lds_dwordx4 v71, s[98:99]
	v_mfma_f32_32x32x16_bf16 v[20:35], v[102:105], v[114:117], v[20:35]
	s_add_i32 m0, s3, 0x4000
	s_nop 0
	global_load_lds_dwordx4 v68, s[100:101]
	s_add_i32 m0, s3, 0x5000
	s_nop 0
	global_load_lds_dwordx4 v69, s[100:101]
	v_mfma_f32_32x32x16_bf16 v[4:19], v[106:109], v[114:117], v[4:19]
	s_add_i32 m0, s3, 0x6000
	s_nop 0
	global_load_lds_dwordx4 v70, s[100:101]
	s_add_i32 m0, s3, 0x7000
	s_nop 0
	global_load_lds_dwordx4 v71, s[100:101]
	s_add_u32 s98, s98, 0x80
	s_addc_u32 s99, s99, 0
	s_add_u32 s100, s100, 0x80
	s_addc_u32 s101, s101, 0
	v_mfma_f32_32x32x16_bf16 v[52:67], v[118:121], v[126:129], v[52:67]
	ds_read_b128 v[168:171], v238 offset:32768
	ds_read_b128 v[172:175], v238 offset:36864
	ds_read_b128 v[176:179], v80 offset:32768
	ds_read_b128 v[180:183], v80 offset:36864
	v_mfma_f32_32x32x16_bf16 v[36:51], v[122:125], v[126:129], v[36:51]
	ds_read_b128 v[184:187], v239 offset:32768
	ds_read_b128 v[188:191], v239 offset:36864
	ds_read_b128 v[192:195], v81 offset:32768
	ds_read_b128 v[204:207], v81 offset:36864
	v_mfma_f32_32x32x16_bf16 v[20:35], v[118:121], v[130:133], v[20:35]
	ds_read_b128 v[82:85], v240 offset:32768
	ds_read_b128 v[86:89], v240 offset:36864
	ds_read_b128 v[90:93], v98 offset:32768
	ds_read_b128 v[218:221], v98 offset:36864
	v_mfma_f32_32x32x16_bf16 v[4:19], v[122:125], v[130:133], v[4:19]
	ds_read_b128 v[222:225], v241 offset:32768
	ds_read_b128 v[226:229], v241 offset:36864
	ds_read_b128 v[230:233], v100 offset:32768
	ds_read_b128 v[234:237], v100 offset:36864
	v_mfma_f32_32x32x16_bf16 v[52:67], v[134:137], v[142:145], v[52:67]
	v_mfma_f32_32x32x16_bf16 v[36:51], v[138:141], v[142:145], v[36:51]
	v_mfma_f32_32x32x16_bf16 v[20:35], v[134:137], v[146:149], v[20:35]
	v_mfma_f32_32x32x16_bf16 v[4:19], v[138:141], v[146:149], v[4:19]
	v_mfma_f32_32x32x16_bf16 v[52:67], v[150:153], v[158:161], v[52:67]
	v_mfma_f32_32x32x16_bf16 v[36:51], v[154:157], v[158:161], v[36:51]
	v_mfma_f32_32x32x16_bf16 v[20:35], v[150:153], v[162:165], v[20:35]
	v_mfma_f32_32x32x16_bf16 v[4:19], v[154:157], v[162:165], v[4:19]
	s_waitcnt vmcnt(0)
	s_waitcnt lgkmcnt(0)
	s_barrier
	v_mfma_f32_32x32x16_bf16 v[52:67], v[168:171], v[176:179], v[52:67]
	s_add_i32 m0, s3, 0x8000
	s_nop 0
	global_load_lds_dwordx4 v68, s[98:99]
	s_add_i32 m0, s3, 0x9000
	s_nop 0
	global_load_lds_dwordx4 v69, s[98:99]
	v_mfma_f32_32x32x16_bf16 v[36:51], v[172:175], v[176:179], v[36:51]
	s_add_i32 m0, s3, 0xa000
	s_nop 0
	global_load_lds_dwordx4 v70, s[98:99]
	s_add_i32 m0, s3, 0xb000
	s_nop 0
	global_load_lds_dwordx4 v71, s[98:99]
	v_mfma_f32_32x32x16_bf16 v[20:35], v[168:171], v[180:183], v[20:35]
	s_add_i32 m0, s3, 0xc000
	s_nop 0
	global_load_lds_dwordx4 v68, s[100:101]
	s_add_i32 m0, s3, 0xd000
	s_nop 0
	global_load_lds_dwordx4 v69, s[100:101]
	v_mfma_f32_32x32x16_bf16 v[4:19], v[172:175], v[180:183], v[4:19]
	s_add_i32 m0, s3, 0xe000
	s_nop 0
	global_load_lds_dwordx4 v70, s[100:101]
	s_add_i32 m0, s3, 0xf000
	s_nop 0
	global_load_lds_dwordx4 v71, s[100:101]
	s_add_u32 s98, s98, 0x80
	s_addc_u32 s99, s99, 0
	s_add_u32 s100, s100, 0x80
	s_addc_u32 s101, s101, 0
	v_mfma_f32_32x32x16_bf16 v[52:67], v[184:187], v[192:195], v[52:67]
	ds_read_b128 v[102:105], v238
	ds_read_b128 v[106:109], v238 offset:4096
	ds_read_b128 v[110:113], v80
	ds_read_b128 v[114:117], v80 offset:4096
	v_mfma_f32_32x32x16_bf16 v[36:51], v[188:191], v[192:195], v[36:51]
	ds_read_b128 v[118:121], v239
	ds_read_b128 v[122:125], v239 offset:4096
	ds_read_b128 v[126:129], v81
	ds_read_b128 v[130:133], v81 offset:4096
	v_mfma_f32_32x32x16_bf16 v[20:35], v[184:187], v[204:207], v[20:35]
	ds_read_b128 v[134:137], v240
	ds_read_b128 v[138:141], v240 offset:4096
	ds_read_b128 v[142:145], v98
	ds_read_b128 v[146:149], v98 offset:4096
	v_mfma_f32_32x32x16_bf16 v[4:19], v[188:191], v[204:207], v[4:19]
	ds_read_b128 v[150:153], v241
	ds_read_b128 v[154:157], v241 offset:4096
	ds_read_b128 v[158:161], v100
	ds_read_b128 v[162:165], v100 offset:4096
	v_mfma_f32_32x32x16_bf16 v[52:67], v[82:85], v[90:93], v[52:67]
	v_mfma_f32_32x32x16_bf16 v[36:51], v[86:89], v[90:93], v[36:51]
	v_mfma_f32_32x32x16_bf16 v[20:35], v[82:85], v[218:221], v[20:35]
	v_mfma_f32_32x32x16_bf16 v[4:19], v[86:89], v[218:221], v[4:19]
	v_mfma_f32_32x32x16_bf16 v[52:67], v[222:225], v[230:233], v[52:67]
	v_mfma_f32_32x32x16_bf16 v[36:51], v[226:229], v[230:233], v[36:51]
	v_mfma_f32_32x32x16_bf16 v[20:35], v[222:225], v[234:237], v[20:35]
	v_mfma_f32_32x32x16_bf16 v[4:19], v[226:229], v[234:237], v[4:19]
	s_add_i32 s2, s2, -1
	s_cmp_lg_u32 s2, 0
	s_cbranch_scc1 .Ldma_oi_loop
	s_waitcnt vmcnt(0)
	s_waitcnt lgkmcnt(0)
	s_barrier
; #define MFMA32(a, b, c) __builtin_amdgcn_mfma_f32_32x32x16_bf16((a), (b), (c), 0, 0, 0)
; template <int MF, int BK, class Epi>
; DI void gemm_phase_t(char* lds, const GemmDesc g, const Epi epi) {
;     ...
;       __builtin_amdgcn_sched_barrier(0);
; #pragma unroll
;       for (int kk = 0; kk < NKK; ++kk)
; #pragma unroll
;         for (int mi = 0; mi < MF; ++mi)
; #pragma unroll
;           for (int ni = 0; ni < 2; ++ni) acc[mi][ni] = MFMA32(bfr[kk][ni], af[kk][mi], acc[mi][ni]);
;     }
;     epi(acc, g.mbase + m0 + wm * (MF * 32), n0 + wn * 64, l31, h);
;   template <int MF> DI void operator()(f32x16 (&acc)[MF][2], int mb, int nb, int l31, int h) const {
;     ...
;     const int which = nb >> 9, head = ((nb >> 6) & 1) * 4 + ((nb >> 7) & 3);
; #pragma unroll
;     for (int mi = 0; mi < MF; ++mi) {
;       const int row = mb + mi * 32 + l31;
;       const bool isl = row < TL;
;       const int b = isl ? row >> 12 : (row - TL) >> 8;
;       const int t = isl ? row & 4095 : (row - TL) & 255;
;       float x[4][8];
; #pragma unroll
;       for (int g4 = 0; g4 < 4; ++g4)
; #pragma unroll
;         for (int k = 0; k < 4; ++k) { x[g4][k] = acc[mi][0][4 * g4 + k]; x[g4][4 + k] = acc[mi][1][4 * g4 + k]; }
;       if (isl) {
;         const float* sr = rope + (t >> 6) * 16 + 8 * h; const float* sc = rope + (t & 63) * 16 + 8 * h;
;         const float4 s1a = *(const float4*)(sr), s1b = *(const float4*)(sr + 4), c1a = *(const float4*)(sr + 1024), c1b = *(const float4*)(sr + 1028);
;         const float4 s2a = *(const float4*)(sc), s2b = *(const float4*)(sc + 4), c2a = *(const float4*)(sc + 1024), c2b = *(const float4*)(sc + 1028);
;         const float s1[8] = {s1a.x, s1a.y, s1a.z, s1a.w, s1b.x, s1b.y, s1b.z, s1b.w}, c1[8] = {c1a.x, c1a.y, c1a.z, c1a.w, c1b.x, c1b.y, c1b.z, c1b.w};
;         const float s2[8] = {s2a.x, s2a.y, s2a.z, s2a.w, s2b.x, s2b.y, s2b.z, s2b.w}, c2[8] = {c2a.x, c2a.y, c2a.z, c2a.w, c2b.x, c2b.y, c2b.z, c2b.w};
; #pragma unroll
;         for (int k = 0; k < 8; ++k) {
;           const float a = x[0][k], bq = x[1][k], cq = x[2][k], dq = x[3][k];
;           x[0][k] = a * c1[k] - bq * s1[k]; x[1][k] = bq * c1[k] + a * s1[k];
;           x[2][k] = cq * c2[k] - dq * s2[k]; x[3][k] = dq * c2[k] + cq * s2[k];
;         }
	v_mfma_f32_32x32x16_bf16 v[52:67], v[102:105], v[110:113], v[52:67]
	v_mfma_f32_32x32x16_bf16 v[36:51], v[106:109], v[110:113], v[36:51]
	v_mfma_f32_32x32x16_bf16 v[20:35], v[102:105], v[114:117], v[20:35]
	v_mfma_f32_32x32x16_bf16 v[4:19], v[106:109], v[114:117], v[4:19]
	v_mfma_f32_32x32x16_bf16 v[52:67], v[118:121], v[126:129], v[52:67]
	ds_read_b128 v[168:171], v238 offset:32768
	ds_read_b128 v[172:175], v238 offset:36864
	ds_read_b128 v[176:179], v80 offset:32768
	ds_read_b128 v[180:183], v80 offset:36864
	v_mfma_f32_32x32x16_bf16 v[36:51], v[122:125], v[126:129], v[36:51]
	ds_read_b128 v[184:187], v239 offset:32768
	ds_read_b128 v[188:191], v239 offset:36864
	ds_read_b128 v[192:195], v81 offset:32768
	ds_read_b128 v[204:207], v81 offset:36864
	v_mfma_f32_32x32x16_bf16 v[20:35], v[118:121], v[130:133], v[20:35]
	ds_read_b128 v[82:85], v240 offset:32768
	ds_read_b128 v[86:89], v240 offset:36864
	ds_read_b128 v[90:93], v98 offset:32768
	ds_read_b128 v[218:221], v98 offset:36864
	v_mfma_f32_32x32x16_bf16 v[4:19], v[122:125], v[130:133], v[4:19]
	ds_read_b128 v[222:225], v241 offset:32768
	ds_read_b128 v[226:229], v241 offset:36864
	ds_read_b128 v[230:233], v100 offset:32768
	ds_read_b128 v[234:237], v100 offset:36864
	v_mfma_f32_32x32x16_bf16 v[52:67], v[134:137], v[142:145], v[52:67]
	v_mfma_f32_32x32x16_bf16 v[36:51], v[138:141], v[142:145], v[36:51]
	v_mfma_f32_32x32x16_bf16 v[20:35], v[134:137], v[146:149], v[20:35]
	v_mfma_f32_32x32x16_bf16 v[4:19], v[138:141], v[146:149], v[4:19]
	v_mfma_f32_32x32x16_bf16 v[52:67], v[150:153], v[158:161], v[52:67]
	v_mfma_f32_32x32x16_bf16 v[36:51], v[154:157], v[158:161], v[36:51]
	v_mfma_f32_32x32x16_bf16 v[20:35], v[150:153], v[162:165], v[20:35]
	v_mfma_f32_32x32x16_bf16 v[4:19], v[154:157], v[162:165], v[4:19]
	s_waitcnt lgkmcnt(0)
	v_mfma_f32_32x32x16_bf16 v[52:67], v[168:171], v[176:179], v[52:67]
	v_mfma_f32_32x32x16_bf16 v[36:51], v[172:175], v[176:179], v[36:51]
	v_mfma_f32_32x32x16_bf16 v[20:35], v[168:171], v[180:183], v[20:35]
	v_mfma_f32_32x32x16_bf16 v[4:19], v[172:175], v[180:183], v[4:19]
	v_mfma_f32_32x32x16_bf16 v[52:67], v[184:187], v[192:195], v[52:67]
	v_mfma_f32_32x32x16_bf16 v[36:51], v[188:191], v[192:195], v[36:51]
	v_mfma_f32_32x32x16_bf16 v[20:35], v[184:187], v[204:207], v[20:35]
	v_mfma_f32_32x32x16_bf16 v[4:19], v[188:191], v[204:207], v[4:19]
	v_mfma_f32_32x32x16_bf16 v[52:67], v[82:85], v[90:93], v[52:67]
	v_mfma_f32_32x32x16_bf16 v[36:51], v[86:89], v[90:93], v[36:51]
	v_mfma_f32_32x32x16_bf16 v[20:35], v[82:85], v[218:221], v[20:35]
	v_mfma_f32_32x32x16_bf16 v[4:19], v[86:89], v[218:221], v[4:19]
	v_mfma_f32_32x32x16_bf16 v[52:67], v[222:225], v[230:233], v[52:67]
	v_mfma_f32_32x32x16_bf16 v[36:51], v[226:229], v[230:233], v[36:51]
	v_mfma_f32_32x32x16_bf16 v[20:35], v[222:225], v[234:237], v[20:35]
	v_mfma_f32_32x32x16_bf16 v[4:19], v[226:229], v[234:237], v[4:19]
	v_add_u32_e32 v70, s21, v95
	v_add_u32_e32 v89, s0, v96
	s_movk_i32 s0, 0x400
	v_cmp_gt_i32_e32 vcc, s0, v70
	v_or_b32_e32 v88, v89, v77
	s_and_saveexec_b64 s[0:1], vcc
	s_xor_b64 s[12:13], exec, s[0:1]
	s_cbranch_execz .LBB0_932
	s_movk_i32 s0, 0x7fff
	s_mov_b32 s2, 0x8000
	s_movk_i32 s14, 0xfdf
	v_cmp_lt_i32_e64 s[0:1], s0, v88
	v_cmp_gt_i32_e64 s[2:3], s2, v88
	v_bitop3_b32 v90, v89, s14, v77 bitop3:0xc8
	v_and_b32_e32 v82, 0xfc0, v89
	s_and_saveexec_b64 s[14:15], s[2:3]
	s_cbranch_execz .LBB0_913
	v_lshlrev_b32_e32 v2, 6, v90
	v_mov_b32_e32 v83, v3
	v_and_b32_e32 v2, 0x7c0, v2
	v_lshl_add_u64 v[68:69], v[78:79], 0, v[82:83]
	v_lshl_add_u64 v[86:87], v[78:79], 0, v[2:3]
	s_mov_b64 s[16:17], 0x1000
	v_lshl_add_u64 v[70:71], v[68:69], 0, s[16:17]
	v_lshl_add_u64 v[92:93], v[86:87], 0, s[16:17]
	s_movk_i32 s16, 0x1000
	global_load_dwordx4 v[102:105], v[68:69], off offset:16
	global_load_dwordx4 v[106:109], v[68:69], off
	v_add_co_u32_e32 v68, vcc, s16, v68
	s_nop 1
	v_addc_co_u32_e32 v69, vcc, 0, v69, vcc
	global_load_dwordx4 v[110:113], v[68:69], off
	global_load_dwordx4 v[114:117], v[70:71], off offset:16
	s_waitcnt vmcnt(2)
	v_pk_mul_f32 v[68:69], v[56:57], v[106:107]
	s_waitcnt vmcnt(1)
	v_pk_mul_f32 v[56:57], v[56:57], v[110:111]
	v_pk_fma_f32 v[84:85], v[52:53], v[110:111], v[68:69] neg_lo:[0,0,1] neg_hi:[0,0,1]
	v_pk_fma_f32 v[56:57], v[52:53], v[106:107], v[56:57]
	global_load_dwordx4 v[68:71], v[86:87], off offset:16
	global_load_dwordx4 v[118:121], v[86:87], off
	v_add_co_u32_e32 v52, vcc, s16, v86
	s_nop 1
	v_addc_co_u32_e32 v53, vcc, 0, v87, vcc
	global_load_dwordx4 v[122:125], v[52:53], off
	global_load_dwordx4 v[126:129], v[92:93], off offset:16
	s_waitcnt vmcnt(2)
	v_pk_mul_f32 v[52:53], v[64:65], v[118:119]
	s_waitcnt vmcnt(1)
	v_pk_fma_f32 v[86:87], v[60:61], v[122:123], v[52:53] neg_lo:[0,0,1] neg_hi:[0,0,1]
	v_pk_mul_f32 v[52:53], v[64:65], v[122:123]
	s_nop 0
	v_pk_fma_f32 v[64:65], v[60:61], v[118:119], v[52:53]
	v_pk_mul_f32 v[52:53], v[58:59], v[108:109]
	v_pk_mul_f32 v[58:59], v[58:59], v[112:113]
	v_pk_fma_f32 v[52:53], v[54:55], v[112:113], v[52:53] neg_lo:[0,0,1] neg_hi:[0,0,1]
	v_pk_fma_f32 v[58:59], v[54:55], v[108:109], v[58:59]
	v_pk_mul_f32 v[54:55], v[66:67], v[120:121]
	s_nop 0
	v_pk_fma_f32 v[60:61], v[62:63], v[124:125], v[54:55] neg_lo:[0,0,1] neg_hi:[0,0,1]
	v_pk_mul_f32 v[54:55], v[66:67], v[124:125]
	s_nop 0
	v_pk_fma_f32 v[66:67], v[62:63], v[120:121], v[54:55]
	v_pk_mul_f32 v[54:55], v[40:41], v[102:103]
	v_pk_mul_f32 v[40:41], v[40:41], v[114:115]
	v_pk_fma_f32 v[54:55], v[36:37], v[114:115], v[54:55] neg_lo:[0,0,1] neg_hi:[0,0,1]
	v_pk_fma_f32 v[40:41], v[36:37], v[102:103], v[40:41]
	v_pk_mul_f32 v[36:37], v[48:49], v[68:69]
	s_waitcnt vmcnt(0)
	v_pk_fma_f32 v[62:63], v[44:45], v[126:127], v[36:37] neg_lo:[0,0,1] neg_hi:[0,0,1]
	v_pk_mul_f32 v[36:37], v[48:49], v[126:127]
	s_nop 0
	v_pk_fma_f32 v[48:49], v[44:45], v[68:69], v[36:37]
	v_pk_mul_f32 v[36:37], v[42:43], v[104:105]
	v_pk_mul_f32 v[42:43], v[42:43], v[116:117]
	v_pk_fma_f32 v[36:37], v[38:39], v[116:117], v[36:37] neg_lo:[0,0,1] neg_hi:[0,0,1]
	v_pk_fma_f32 v[42:43], v[38:39], v[104:105], v[42:43]
	v_pk_mul_f32 v[38:39], v[50:51], v[70:71]
	s_nop 0
	v_pk_fma_f32 v[44:45], v[46:47], v[128:129], v[38:39] neg_lo:[0,0,1] neg_hi:[0,0,1]
	v_pk_mul_f32 v[38:39], v[50:51], v[128:129]
	s_nop 0
	v_pk_fma_f32 v[50:51], v[46:47], v[70:71], v[38:39]
	v_mov_b32_e32 v38, v36
	v_mov_b32_e32 v39, v37
	v_mov_b32_e32 v36, v54
	v_mov_b32_e32 v37, v55
	v_mov_b32_e32 v54, v52
	v_mov_b32_e32 v55, v53
	v_mov_b32_e32 v52, v84
	v_mov_b32_e32 v53, v85
	v_mov_b32_e32 v46, v44
	v_mov_b32_e32 v47, v45
	v_mov_b32_e32 v44, v62
	v_mov_b32_e32 v45, v63
	v_mov_b32_e32 v62, v60
	v_mov_b32_e32 v63, v61
	v_mov_b32_e32 v60, v86
	v_mov_b32_e32 v61, v87
